# v20 + attention softmax: the 32 s_nop pads in front of the bf16 pack converts removed (their transcendental producers are >= 3 instructions upstream)
# baseline (speedup 1.0000x reference)
; #define LAS __attribute__((address_space(3)))
; __device__ __forceinline__ void attn_phase(LAS unsigned char* lds, const bf16_t* Q, const bf16_t* Kb, const bf16_t* VT, const bf16_t* Z, const float* kpart, bf16_t* Y, int G, int bid) {
;     ...
;                     if (i == 0) {
;                         float mx = s0[0];
; #pragma unroll
;                         for (int j = 1; j < 16; ++j) mx = fmaxf(mx, s0[j]);
; #pragma unroll
;                         for (int j = 0; j < 16; ++j) mx = fmaxf(mx, s1[j]);
;                         mx = fmaxf(mx, __shfl_xor(mx, 32));
;                         mrow = mx;
; #pragma unroll
;                         for (int j = 0; j < 16; ++j) { s0[j] -= mx; s1[j] -= mx; }
;                     }
;                     float ps = 0.f;
; #pragma unroll
;                     for (int j = 0; j < 16; ++j) { s0[j] = __builtin_amdgcn_exp2f(s0[j]); s1[j] = __builtin_amdgcn_exp2f(s1[j]); ps += s0[j] + s1[j]; }
;                     lsum += ps;
;                     bf16x8 P[4];
;                     { u32x4 w;
;                       w.x = cvt_pk_bf16_t(s0[0], s0[1]); w.y = cvt_pk_bf16_t(s0[2], s0[3]); w.z = cvt_pk_bf16_t(s0[4], s0[5]); w.w = cvt_pk_bf16_t(s0[6], s0[7]); __builtin_memcpy(&P[0], &w, 16);
;                       w.x = cvt_pk_bf16_t(s0[8], s0[9]); w.y = cvt_pk_bf16_t(s0[10], s0[11]); w.z = cvt_pk_bf16_t(s0[12], s0[13]); w.w = cvt_pk_bf16_t(s0[14], s0[15]); __builtin_memcpy(&P[1], &w, 16);
;                       w.x = cvt_pk_bf16_t(s1[0], s1[1]); w.y = cvt_pk_bf16_t(s1[2], s1[3]); w.z = cvt_pk_bf16_t(s1[4], s1[5]); w.w = cvt_pk_bf16_t(s1[6], s1[7]); __builtin_memcpy(&P[2], &w, 16);
;                       w.x = cvt_pk_bf16_t(s1[8], s1[9]); w.y = cvt_pk_bf16_t(s1[10], s1[11]); w.z = cvt_pk_bf16_t(s1[12], s1[13]); w.w = cvt_pk_bf16_t(s1[14], s1[15]); __builtin_memcpy(&P[3], &w, 16); }
;                     {
;                         const LAS unsigned char* vp = vb_ + qr * VSTR + hh * 16;
;     ...
;                         bf16x8 v0a = *(const LAS bf16x8*)ATT_VADDR(0, 0), v0c = *(const LAS bf16x8*)ATT_VADDR(0, 1);
;                         bf16x8 v1a = *(const LAS bf16x8*)ATT_VADDR(2, 0), v1c = *(const LAS bf16x8*)ATT_VADDR(2, 1);
;                         bf16x8 v2a = *(const LAS bf16x8*)ATT_VADDR(4, 0), v2c = *(const LAS bf16x8*)ATT_VADDR(4, 1);
; #pragma unroll
;                         for (int st = 0; st < 16; st += 2) {
.LBB0_662:
	s_nop 7
	v_max_f32_e32 v32, v1, v1
	v_max_f32_e32 v33, v0, v0
	v_max_f32_e32 v32, v33, v32
	v_max3_f32 v32, v32, v2, v3
	v_max3_f32 v32, v32, v4, v5
	v_max3_f32 v32, v32, v6, v7
	v_max3_f32 v32, v32, v8, v9
	v_max3_f32 v32, v32, v10, v11
	v_max3_f32 v32, v32, v12, v13
	v_max3_f32 v32, v32, v14, v15
	v_max3_f32 v32, v32, v16, v17
	v_max3_f32 v32, v32, v18, v19
	v_max3_f32 v32, v32, v20, v21
	v_max3_f32 v32, v32, v22, v23
	v_and_b32_e32 v34, 64, v175
	v_max3_f32 v32, v32, v24, v25
	v_xor_b32_e32 v33, 32, v175
	v_add_u32_e32 v34, 64, v34
	v_max3_f32 v32, v32, v26, v27
	v_cmp_lt_i32_e32 vcc, v33, v34
	v_max3_f32 v32, v32, v28, v29
	v_max3_f32 v32, v32, v30, v31
	v_cndmask_b32_e32 v33, v175, v33, vcc
	v_lshlrev_b32_e32 v33, 2, v33
	ds_bpermute_b32 v33, v33, v32
	s_waitcnt lgkmcnt(0)
	v_max_f32_e32 v33, v33, v33
	v_max_f32_e32 v88, v32, v33
	v_sub_f32_e32 v16, v16, v88
	v_sub_f32_e32 v0, v0, v88
	v_sub_f32_e32 v17, v17, v88
	v_sub_f32_e32 v1, v1, v88
	v_exp_f32_e32 v39, v0
	v_exp_f32_e32 v40, v16
	v_sub_f32_e32 v18, v18, v88
	v_sub_f32_e32 v2, v2, v88
	v_exp_f32_e32 v44, v1
	v_exp_f32_e32 v45, v17
	v_sub_f32_e32 v19, v19, v88
	v_sub_f32_e32 v3, v3, v88
	v_exp_f32_e32 v46, v2
	v_exp_f32_e32 v47, v18
	v_sub_f32_e32 v20, v20, v88
	v_sub_f32_e32 v21, v21, v88
	v_sub_f32_e32 v4, v4, v88
	v_sub_f32_e32 v32, v5, v88
	v_exp_f32_e32 v48, v3
	v_exp_f32_e32 v49, v19
	v_add_f32_e32 v0, v39, v40
	v_exp_f32_e32 v3, v4
	v_exp_f32_e32 v5, v20
	v_exp_f32_e32 v2, v32
	v_exp_f32_e32 v4, v21
	v_add_f32_e32 v0, 0, v0
	v_add_f32_e32 v1, v44, v45
	v_add_f32_e32 v0, v1, v0
	v_add_f32_e32 v1, v46, v47
	v_add_f32_e32 v0, v1, v0
	v_add_f32_e32 v1, v48, v49
	v_sub_f32_e32 v22, v22, v88
	v_sub_f32_e32 v23, v23, v88
	v_sub_f32_e32 v6, v6, v88
	v_sub_f32_e32 v33, v7, v88
	v_add_f32_e32 v7, v1, v0
	v_pk_add_f32 v[0:1], v[2:3], v[4:5]
	v_sub_f32_e32 v34, v8, v88
	v_sub_f32_e32 v35, v9, v88
	v_add_f32_e32 v1, v1, v7
	v_exp_f32_e32 v7, v6
	v_exp_f32_e32 v9, v22
	v_exp_f32_e32 v6, v33
	v_exp_f32_e32 v8, v23
	v_sub_f32_e32 v24, v24, v88
	v_sub_f32_e32 v25, v25, v88
	v_sub_f32_e32 v36, v10, v88
	v_sub_f32_e32 v37, v11, v88
	v_sub_f32_e32 v38, v12, v88
	v_sub_f32_e32 v41, v13, v88
	v_exp_f32_e32 v11, v34
	v_exp_f32_e32 v13, v24
	v_exp_f32_e32 v10, v35
	v_exp_f32_e32 v12, v25
	v_sub_f32_e32 v42, v14, v88
	v_add_f32_e32 v14, v0, v1
	v_pk_add_f32 v[0:1], v[6:7], v[8:9]
	v_sub_f32_e32 v26, v26, v88
	v_add_f32_e32 v1, v1, v14
	v_sub_f32_e32 v27, v27, v88
	v_add_f32_e32 v14, v0, v1
	v_pk_add_f32 v[0:1], v[10:11], v[12:13]
	v_sub_f32_e32 v43, v15, v88
	v_add_f32_e32 v1, v1, v14
	v_exp_f32_e32 v15, v36
	v_exp_f32_e32 v17, v26
	v_exp_f32_e32 v14, v37
	v_exp_f32_e32 v16, v27
	v_sub_f32_e32 v28, v28, v88
	v_sub_f32_e32 v29, v29, v88
	v_exp_f32_e32 v19, v38
	v_exp_f32_e32 v21, v28
	v_exp_f32_e32 v18, v41
	v_exp_f32_e32 v20, v29
	v_add_f32_e32 v22, v0, v1
	v_pk_add_f32 v[0:1], v[14:15], v[16:17]
	v_sub_f32_e32 v30, v30, v88
	v_add_f32_e32 v1, v1, v22
	v_sub_f32_e32 v31, v31, v88
	v_add_f32_e32 v0, v0, v1
	v_pk_add_f32 v[32:33], v[18:19], v[20:21]
	v_exp_f32_e32 v35, v42
	v_add_f32_e32 v33, v33, v0
	v_exp_f32_e32 v37, v30
	v_exp_f32_e32 v34, v43
	v_exp_f32_e32 v36, v31
	v_cvt_pk_bf16_f32 v0, v39, v44
	v_cvt_pk_bf16_f32 v1, v46, v48
	v_cvt_pk_bf16_f32 v2, v3, v2
	v_cvt_pk_bf16_f32 v3, v7, v6
	v_cvt_pk_bf16_f32 v90, v11, v10
	v_cvt_pk_bf16_f32 v91, v15, v14
	v_cvt_pk_bf16_f32 v92, v19, v18
	v_cvt_pk_bf16_f32 v93, v35, v34
	v_cvt_pk_bf16_f32 v128, v40, v45
	v_cvt_pk_bf16_f32 v129, v47, v49
	v_cvt_pk_bf16_f32 v130, v5, v4
	v_cvt_pk_bf16_f32 v131, v9, v8
	v_cvt_pk_bf16_f32 v132, v13, v12
	v_cvt_pk_bf16_f32 v133, v17, v16
	v_cvt_pk_bf16_f32 v134, v21, v20
	v_cvt_pk_bf16_f32 v135, v37, v36
	ds_read_b128 v[4:7], v163 offset:34816
	ds_read_b128 v[8:11], v163 offset:34848
	ds_read_b128 v[12:15], v163 offset:34880
	ds_read_b128 v[16:19], v163 offset:34912
	ds_read_b128 v[20:23], v163 offset:39424
	ds_read_b128 v[24:27], v163 offset:39456
	ds_read_b128 v[28:31], v163 offset:39488
	ds_read_b128 v[136:139], v163 offset:39520
	v_add_f32_e32 v38, v32, v33
	v_pk_add_f32 v[32:33], v[34:35], v[36:37]
	s_nop 0
	v_add_f32_e32 v33, v33, v38
	v_add_f32_e32 v89, v32, v33
	s_waitcnt lgkmcnt(7)
	v_mfma_f32_32x32x16_bf16 v[48:63], v[4:7], v[0:3], 0
	s_waitcnt lgkmcnt(6)
	v_mfma_f32_32x32x16_bf16 v[48:63], v[8:11], v[90:93], v[48:63]
	ds_read_b128 v[4:7], v163 offset:44032
	ds_read_b128 v[8:11], v163 offset:44064
	s_waitcnt lgkmcnt(7)
	v_mfma_f32_32x32x16_bf16 v[48:63], v[12:15], v[128:131], v[48:63]
	s_waitcnt lgkmcnt(6)
	v_mfma_f32_32x32x16_bf16 v[48:63], v[16:19], v[132:135], v[48:63]
	ds_read_b128 v[12:15], v163 offset:44096
	ds_read_b128 v[140:143], v163 offset:44128
	s_waitcnt lgkmcnt(7)
	v_mfma_f32_32x32x16_bf16 v[32:47], v[20:23], v[0:3], 0
	s_waitcnt lgkmcnt(6)
	v_mfma_f32_32x32x16_bf16 v[32:47], v[24:27], v[90:93], v[32:47]
	ds_read_b128 v[216:219], v163 offset:48640
	ds_read_b128 v[220:223], v163 offset:48672
	s_waitcnt lgkmcnt(7)
	v_mfma_f32_32x32x16_bf16 v[32:47], v[28:31], v[128:131], v[32:47]
	s_waitcnt lgkmcnt(6)
	v_mfma_f32_32x32x16_bf16 v[32:47], v[136:139], v[132:135], v[32:47]
	ds_read_b128 v[136:139], v163 offset:48704
	ds_read_b128 v[224:227], v163 offset:48736
	s_waitcnt lgkmcnt(7)
	v_mfma_f32_32x32x16_bf16 v[16:31], v[4:7], v[0:3], 0
	s_waitcnt lgkmcnt(6)
	v_mfma_f32_32x32x16_bf16 v[16:31], v[8:11], v[90:93], v[16:31]
	s_waitcnt lgkmcnt(5)
	v_mfma_f32_32x32x16_bf16 v[16:31], v[12:15], v[128:131], v[16:31]
	s_waitcnt lgkmcnt(4)
	v_mfma_f32_32x32x16_bf16 v[16:31], v[140:143], v[132:135], v[16:31]
	s_waitcnt lgkmcnt(3)
	v_mfma_f32_32x32x16_bf16 v[0:15], v[216:219], v[0:3], 0
	s_waitcnt lgkmcnt(2)
	v_mfma_f32_32x32x16_bf16 v[0:15], v[220:223], v[90:93], v[0:15]
	s_waitcnt lgkmcnt(1)
	v_mfma_f32_32x32x16_bf16 v[0:15], v[136:139], v[128:131], v[0:15]
	s_waitcnt lgkmcnt(0)
	v_mfma_f32_32x32x16_bf16 v[0:15], v[224:227], v[132:135], v[0:15]
	v_add_f32_e32 v215, 0, v89
	s_mov_b64 s[8:9], 0

; #define LAS __attribute__((address_space(3)))
; __device__ __forceinline__ void attn_phase(LAS unsigned char* lds, const bf16_t* Q, const bf16_t* Kb, const bf16_t* VT, const bf16_t* Z, const float* kpart, bf16_t* Y, int G, int bid) {
;     ...
;                     float ps = 0.f;
; #pragma unroll
;                     for (int j = 0; j < 16; ++j) { s0[j] = __builtin_amdgcn_exp2f(s0[j]); s1[j] = __builtin_amdgcn_exp2f(s1[j]); ps += s0[j] + s1[j]; }
;                     lsum += ps;
;                     bf16x8 P[4];
;                     { u32x4 w;
;                       w.x = cvt_pk_bf16_t(s0[0], s0[1]); w.y = cvt_pk_bf16_t(s0[2], s0[3]); w.z = cvt_pk_bf16_t(s0[4], s0[5]); w.w = cvt_pk_bf16_t(s0[6], s0[7]); __builtin_memcpy(&P[0], &w, 16);
;                       w.x = cvt_pk_bf16_t(s0[8], s0[9]); w.y = cvt_pk_bf16_t(s0[10], s0[11]); w.z = cvt_pk_bf16_t(s0[12], s0[13]); w.w = cvt_pk_bf16_t(s0[14], s0[15]); __builtin_memcpy(&P[1], &w, 16);
;                       w.x = cvt_pk_bf16_t(s1[0], s1[1]); w.y = cvt_pk_bf16_t(s1[2], s1[3]); w.z = cvt_pk_bf16_t(s1[4], s1[5]); w.w = cvt_pk_bf16_t(s1[6], s1[7]); __builtin_memcpy(&P[2], &w, 16);
;                       w.x = cvt_pk_bf16_t(s1[8], s1[9]); w.y = cvt_pk_bf16_t(s1[10], s1[11]); w.z = cvt_pk_bf16_t(s1[12], s1[13]); w.w = cvt_pk_bf16_t(s1[14], s1[15]); __builtin_memcpy(&P[3], &w, 16); }
;                     {
;                         const LAS unsigned char* vp = vb_ + qr * VSTR + hh * 16;
;     ...
;                         bf16x8 v0a = *(const LAS bf16x8*)ATT_VADDR(0, 0), v0c = *(const LAS bf16x8*)ATT_VADDR(0, 1);
;                         bf16x8 v1a = *(const LAS bf16x8*)ATT_VADDR(2, 0), v1c = *(const LAS bf16x8*)ATT_VADDR(2, 1);
;                         bf16x8 v2a = *(const LAS bf16x8*)ATT_VADDR(4, 0), v2c = *(const LAS bf16x8*)ATT_VADDR(4, 1);
; #pragma unroll
;                         for (int st = 0; st < 16; st += 2) {
;                             const int dt = st >> 2, kk = st & 3;
;                             bf16x8 na = v2a, nc = v2c;
;                             if (st < 10) { na = *(const LAS bf16x8*)ATT_VADDR(st + 6, 0); nc = *(const LAS bf16x8*)ATT_VADDR(st + 6, 1); }
;                             __builtin_amdgcn_sched_barrier(0);
;                             O[dt] = MFMA32(v0a, P[kk], O[dt]); O[dt] = MFMA32(v0c, P[kk + 1], O[dt]);
;                             __builtin_amdgcn_sched_barrier(0);
.LBB0_674:
	s_nop 3
	v_exp_f32_e32 v189, v80
	s_nop 0
	v_exp_f32_e32 v217, v64
	v_exp_f32_e32 v218, v81
	v_exp_f32_e32 v219, v65
	v_exp_f32_e32 v220, v82
	v_exp_f32_e32 v221, v66
	v_exp_f32_e32 v222, v83
	v_exp_f32_e32 v223, v67
	v_add_f32_e32 v64, v189, v217
	v_exp_f32_e32 v67, v84
	v_exp_f32_e32 v81, v68
	v_exp_f32_e32 v66, v85
	v_exp_f32_e32 v80, v69
	v_add_f32_e32 v64, 0, v64
	v_add_f32_e32 v65, v218, v219
	v_add_f32_e32 v64, v65, v64
	v_add_f32_e32 v65, v220, v221
	v_add_f32_e32 v64, v65, v64
	v_add_f32_e32 v65, v222, v223
	v_add_f32_e32 v68, v65, v64
	v_pk_add_f32 v[64:65], v[66:67], v[80:81]
	v_exp_f32_e32 v69, v86
	v_add_f32_e32 v65, v65, v68
	v_exp_f32_e32 v83, v70
	v_exp_f32_e32 v68, v87
	v_exp_f32_e32 v82, v71
	v_exp_f32_e32 v71, v88
	v_exp_f32_e32 v85, v72
	v_exp_f32_e32 v70, v89
	v_exp_f32_e32 v84, v73
	v_add_f32_e32 v224, v64, v65
	v_pk_add_f32 v[64:65], v[68:69], v[82:83]
	v_exp_f32_e32 v73, v90
	v_add_f32_e32 v65, v65, v224
	v_add_f32_e32 v72, v64, v65
	v_pk_add_f32 v[64:65], v[70:71], v[84:85]
	v_exp_f32_e32 v87, v74
	v_add_f32_e32 v65, v65, v72
	v_exp_f32_e32 v72, v91
	v_exp_f32_e32 v86, v75
	v_exp_f32_e32 v75, v92
	v_exp_f32_e32 v89, v76
	v_exp_f32_e32 v74, v93
	v_exp_f32_e32 v88, v77
	v_add_f32_e32 v224, v64, v65
	v_pk_add_f32 v[64:65], v[72:73], v[86:87]
	s_mulk_i32 s10, 0x4800
	v_add_f32_e32 v65, v65, v224
	v_add_f32_e32 v64, v64, v65
	v_pk_add_f32 v[234:235], v[74:75], v[88:89]
	v_exp_f32_e32 v237, v94
	v_add_f32_e32 v235, v235, v64
	v_cvt_pk_bf16_f32 v64, v189, v218
	v_add_u32_e32 v189, s10, v163
	v_exp_f32_e32 v239, v78
	v_exp_f32_e32 v236, v95
	v_exp_f32_e32 v238, v79
	v_cvt_pk_bf16_f32 v65, v220, v222
	v_cvt_pk_bf16_f32 v66, v67, v66
	v_cvt_pk_bf16_f32 v67, v69, v68
	v_cvt_pk_bf16_f32 v68, v71, v70
	v_cvt_pk_bf16_f32 v69, v73, v72
	v_cvt_pk_bf16_f32 v70, v75, v74
	v_cvt_pk_bf16_f32 v71, v237, v236
	v_cvt_pk_bf16_f32 v72, v217, v219
	v_cvt_pk_bf16_f32 v73, v221, v223
	v_cvt_pk_bf16_f32 v74, v81, v80
	v_cvt_pk_bf16_f32 v75, v83, v82
	v_cvt_pk_bf16_f32 v76, v85, v84
	v_cvt_pk_bf16_f32 v77, v87, v86
	v_cvt_pk_bf16_f32 v78, v89, v88
	v_cvt_pk_bf16_f32 v79, v239, v238
	ds_read_b128 v[80:83], v189 offset:34816
	ds_read_b128 v[84:87], v189 offset:34848
	ds_read_b128 v[88:91], v189 offset:34880
	ds_read_b128 v[92:95], v189 offset:34912
	ds_read_b128 v[218:221], v189 offset:39424
	ds_read_b128 v[222:225], v189 offset:39456
	ds_read_b128 v[226:229], v189 offset:39488
	ds_read_b128 v[230:233], v189 offset:39520
	v_add_f32_e32 v217, v234, v235
	v_pk_add_f32 v[234:235], v[236:237], v[238:239]
	s_nop 0
	v_add_f32_e32 v217, v235, v217
	v_add_f32_e32 v217, v234, v217
	s_waitcnt lgkmcnt(7)
	v_mfma_f32_32x32x16_bf16 v[48:63], v[80:83], v[64:67], v[48:63]
	s_waitcnt lgkmcnt(6)
	v_mfma_f32_32x32x16_bf16 v[48:63], v[84:87], v[68:71], v[48:63]
	ds_read_b128 v[80:83], v189 offset:44032
	ds_read_b128 v[84:87], v189 offset:44064
	s_waitcnt lgkmcnt(7)
	v_mfma_f32_32x32x16_bf16 v[48:63], v[88:91], v[72:75], v[48:63]
	s_waitcnt lgkmcnt(6)
	v_mfma_f32_32x32x16_bf16 v[48:63], v[92:95], v[76:79], v[48:63]
	ds_read_b128 v[88:91], v189 offset:44096
	ds_read_b128 v[92:95], v189 offset:44128
	s_waitcnt lgkmcnt(7)
	v_mfma_f32_32x32x16_bf16 v[32:47], v[218:221], v[64:67], v[32:47]
	s_waitcnt lgkmcnt(6)
	v_mfma_f32_32x32x16_bf16 v[32:47], v[222:225], v[68:71], v[32:47]
	ds_read_b128 v[218:221], v189 offset:48640
	ds_read_b128 v[222:225], v189 offset:48672
	s_waitcnt lgkmcnt(7)
	v_mfma_f32_32x32x16_bf16 v[32:47], v[226:229], v[72:75], v[32:47]
	s_waitcnt lgkmcnt(6)
	v_mfma_f32_32x32x16_bf16 v[32:47], v[230:233], v[76:79], v[32:47]
	ds_read_b128 v[226:229], v189 offset:48704
	ds_read_b128 v[230:233], v189 offset:48736
	s_waitcnt lgkmcnt(7)
	v_mfma_f32_32x32x16_bf16 v[16:31], v[80:83], v[64:67], v[16:31]
	s_waitcnt lgkmcnt(6)
	v_mfma_f32_32x32x16_bf16 v[16:31], v[84:87], v[68:71], v[16:31]
	s_waitcnt lgkmcnt(5)
	v_mfma_f32_32x32x16_bf16 v[16:31], v[88:91], v[72:75], v[16:31]
	s_waitcnt lgkmcnt(4)
	v_mfma_f32_32x32x16_bf16 v[16:31], v[92:95], v[76:79], v[16:31]
	s_waitcnt lgkmcnt(3)
	v_mfma_f32_32x32x16_bf16 v[0:15], v[218:221], v[64:67], v[0:15]
	s_waitcnt lgkmcnt(2)
	v_mfma_f32_32x32x16_bf16 v[0:15], v[222:225], v[68:71], v[0:15]
	s_waitcnt lgkmcnt(1)
	v_mfma_f32_32x32x16_bf16 v[0:15], v[226:229], v[72:75], v[0:15]
	s_waitcnt lgkmcnt(0)
	v_mfma_f32_32x32x16_bf16 v[0:15], v[230:233], v[76:79], v[0:15]
	v_add_f32_e32 v215, v215, v217
